# MT=8 phases 2 and 11: XCD-balanced tile mapping (114 / 168 tiles per XCD)
# baseline (speedup 1.0000x reference)
.LBB0_257:
	s_ashr_i32 s4, s28, 6
	s_lshr_b32 s5, s84, 3
	s_cmp_eq_u32 s4, 1
	s_cbranch_scc1 .Lxb2_ns
	s_lshr_b32 s6, s5, 2
	s_lshr_b32 s7, s5, 5
	s_xor_b32 s6, s6, s7
	s_and_b32 s6, s6, 1
	s_mul_i32 s6, s6, 36
	s_xor_b32 s5, s5, s6
.Lxb2_ns:
	s_lshl_b32 s6, s4, 6
	s_add_i32 s5, s5, s6
	s_mov_b32 s8, 2
	s_cmp_gt_i32 s5, 113
	s_cbranch_scc1 .LBB0_344
	s_and_b32 s6, s84, 7
	s_mul_i32 s6, s6, 114
	s_add_i32 s5, s5, s6
	s_cmp_gt_i32 s5, 455
	s_cselect_b32 s7, 1, 0
	s_mul_i32 s6, s7, 456
	s_sub_i32 s5, s5, s6
	s_lshr_b32 s6, s5, 3
	s_and_b32 s5, s5, 7
	s_lshl_b32 s7, s7, 3
	s_lshr_b32 s9, s6, 3
	s_add_i32 s7, s7, s9
	s_and_b32 s6, s6, 7
	s_lshl_b32 s6, s6, 3
	s_or_b32 s6, s6, s5
	s_lshl_b32 s4, s4, 6
	s_or_b32 s28, s4, s6
	s_mov_b32 s23, s28
	s_mov_b32 s4, s7
	s_ashr_i32 s5, s4, 31
	s_lshr_b32 s5, s5, 29
	s_add_i32 s7, s4, s5
	s_and_b32 s5, s7, -8
	s_and_b32 s6, s28, 7
	s_or_b32 s6, s5, s6
	s_sub_i32 s5, s4, s5
	s_lshl_b32 s8, s5, 3
	s_bfe_u32 s5, s28, 0x30003
	s_or_b32 s9, s8, s5
	s_cmp_gt_i32 s6, 15
	s_cselect_b64 s[16:17], -1, 0
	s_cmp_gt_i32 s9, 56
	s_cselect_b64 s[18:19], -1, 0
	s_or_b64 s[16:17], s[16:17], s[18:19]
	s_mov_b32 s8, 4
	s_and_b64 vcc, exec, s[16:17]
	s_cbranch_vccnz .LBB0_344
	s_lshl_b32 s6, s6, 8
	s_ashr_i32 s29, s7, 3
	s_and_b32 s7, s23, 7
	s_addk_i32 s6, 0x2000
	s_lshl_b32 s30, s7, 8
	s_ashr_i32 s7, s6, 31
	s_lshl_b64 s[18:19], s[6:7], 11
	v_lshl_add_u64 v[48:49], v[186:187], 0, s[18:19]
	v_add_co_u32_e32 v50, vcc, 0x10000, v48
	s_lshl_b32 s16, s9, 7
	s_nop 0
	v_addc_co_u32_e32 v51, vcc, 0, v49, vcc
	v_add_co_u32_e32 v52, vcc, 0x20000, v48
	s_ashr_i32 s17, s16, 31
	s_nop 0
	v_addc_co_u32_e32 v53, vcc, 0, v49, vcc
	v_add_co_u32_e32 v54, vcc, 0x30000, v48
	s_lshl_b64 s[8:9], s[16:17], 11
	s_nop 0
	v_addc_co_u32_e32 v55, vcc, 0, v49, vcc
	v_add_co_u32_e32 v56, vcc, 0x40000, v48
	v_lshl_add_u64 v[68:69], v[188:189], 0, s[8:9]
	s_nop 0
	v_addc_co_u32_e32 v57, vcc, 0, v49, vcc
	v_add_co_u32_e32 v58, vcc, 0x50000, v48
	s_mov_b32 s7, 0x10000
	s_nop 0
	v_addc_co_u32_e32 v59, vcc, 0, v49, vcc
	v_add_co_u32_e32 v64, vcc, 0x60000, v48
	s_lshl_b32 s4, s4, 3
	s_nop 0
	v_addc_co_u32_e32 v65, vcc, 0, v49, vcc
	v_add_co_u32_e32 v66, vcc, 0x70000, v48
	s_or_b32 s4, s4, s5
	s_nop 0
	v_addc_co_u32_e32 v67, vcc, 0, v49, vcc
	v_add_co_u32_e32 v70, vcc, s7, v68
	s_mov_b32 s7, 0x20000
	s_nop 0
	v_addc_co_u32_e32 v71, vcc, 0, v69, vcc
	v_add_co_u32_e32 v72, vcc, s7, v68
	s_mov_b32 s7, 0x30000
	s_nop 0
	v_addc_co_u32_e32 v73, vcc, 0, v69, vcc
	v_add_co_u32_e32 v74, vcc, s7, v68
	s_lshl_b32 s7, s29, 11
	s_nop 0
	v_addc_co_u32_e32 v75, vcc, 0, v69, vcc
	s_nop 0
	v_readfirstlane_b32 s98, v48
	v_readfirstlane_b32 s99, v49
	s_nop 0
	v_readfirstlane_b32 s100, v68
	v_readfirstlane_b32 s101, v69
	s_lshl_b32 s5, s29, 6
	s_or_b32 s7, s7, s30
	s_sub_i32 s4, s4, s5
	s_add_i32 s8, s7, 0x2000
	s_lshl_b32 s4, s4, 7
	s_ashr_i32 s9, s8, 31
	s_ashr_i32 s5, s4, 31
	s_lshl_b64 s[8:9], s[8:9], 11
	s_lshl_b64 s[18:19], s[4:5], 11
	v_mov_b32_e32 v60, 0
	s_mov_b64 s[4:5], 0
	v_mov_b32_e32 v61, v60
	v_mov_b32_e32 v62, v60
	v_mov_b32_e32 v63, v60
	v_mov_b32_e32 v16, v60
	v_mov_b32_e32 v17, v60
	v_mov_b32_e32 v18, v60
	v_mov_b32_e32 v19, v60
	v_mov_b32_e32 v20, v60
	v_mov_b32_e32 v21, v60
	v_mov_b32_e32 v22, v60
	v_mov_b32_e32 v23, v60
	v_mov_b32_e32 v28, v60
	v_mov_b32_e32 v29, v60
	v_mov_b32_e32 v30, v60
	v_mov_b32_e32 v31, v60
	v_mov_b32_e32 v40, v60
	v_mov_b32_e32 v41, v60
	v_mov_b32_e32 v42, v60
	v_mov_b32_e32 v43, v60
	v_mov_b32_e32 v44, v60
	v_mov_b32_e32 v45, v60
	v_mov_b32_e32 v46, v60
	v_mov_b32_e32 v47, v60
	v_mov_b32_e32 v4, v60
	v_mov_b32_e32 v5, v60
	v_mov_b32_e32 v6, v60
	v_mov_b32_e32 v7, v60
	v_mov_b32_e32 v0, v60
	v_mov_b32_e32 v1, v60
	v_mov_b32_e32 v2, v60
	v_mov_b32_e32 v3, v60
	v_mov_b32_e32 v32, v60
	v_mov_b32_e32 v33, v60
	v_mov_b32_e32 v34, v60
	v_mov_b32_e32 v35, v60
	v_mov_b32_e32 v24, v60
	v_mov_b32_e32 v25, v60
	v_mov_b32_e32 v26, v60
	v_mov_b32_e32 v27, v60
	v_mov_b32_e32 v12, v60
	v_mov_b32_e32 v13, v60
	v_mov_b32_e32 v14, v60
	v_mov_b32_e32 v15, v60
	v_mov_b32_e32 v8, v60
	v_mov_b32_e32 v9, v60
	v_mov_b32_e32 v10, v60
	v_mov_b32_e32 v11, v60
	v_mov_b32_e32 v36, v60
	v_mov_b32_e32 v37, v60
	v_mov_b32_e32 v38, v60
	v_mov_b32_e32 v39, v60
	v_mov_b32_e32 v56, v60
	v_mov_b32_e32 v57, v60
	v_mov_b32_e32 v58, v60
	v_mov_b32_e32 v59, v60
	v_mov_b32_e32 v52, v60
	v_mov_b32_e32 v53, v60
	v_mov_b32_e32 v54, v60
	v_mov_b32_e32 v55, v60
	v_mov_b32_e32 v48, v60
	v_mov_b32_e32 v49, v60
	v_mov_b32_e32 v50, v60
	v_mov_b32_e32 v51, v60
	v_mov_b32_e32 v68, v60
	v_mov_b32_e32 v69, v60
	v_mov_b32_e32 v70, v60
	v_mov_b32_e32 v71, v60
	v_mov_b32_e32 v72, v60
	v_mov_b32_e32 v73, v60
	v_mov_b32_e32 v74, v60
	v_mov_b32_e32 v75, v60
	v_mov_b32_e32 v64, v60
	v_mov_b32_e32 v65, v60
	v_mov_b32_e32 v66, v60
	v_mov_b32_e32 v67, v60
	v_mov_b32_e32 v76, v60
	v_mov_b32_e32 v77, v60
	v_mov_b32_e32 v78, v60
	v_mov_b32_e32 v79, v60
	v_mov_b32_e32 v80, v60
	v_mov_b32_e32 v81, v60
	v_mov_b32_e32 v82, v60
	v_mov_b32_e32 v83, v60
	v_mov_b32_e32 v84, v60
	v_mov_b32_e32 v85, v60
	v_mov_b32_e32 v86, v60
	v_mov_b32_e32 v87, v60
	v_mov_b32_e32 v88, v60
	v_mov_b32_e32 v89, v60
	v_mov_b32_e32 v90, v60
	v_mov_b32_e32 v91, v60
	v_mov_b32_e32 v92, v60
	v_mov_b32_e32 v93, v60
	v_mov_b32_e32 v94, v60
	v_mov_b32_e32 v95, v60
	v_mov_b32_e32 v96, v60
	v_mov_b32_e32 v97, v60
	v_mov_b32_e32 v98, v60
	v_mov_b32_e32 v99, v60
	v_mov_b32_e32 v100, v60
	v_mov_b32_e32 v101, v60
	v_mov_b32_e32 v102, v60
	v_mov_b32_e32 v103, v60
	v_mov_b32_e32 v104, v60
	v_mov_b32_e32 v105, v60
	v_mov_b32_e32 v106, v60
	v_mov_b32_e32 v107, v60
	v_mov_b32_e32 v108, v60
	v_mov_b32_e32 v109, v60
	v_mov_b32_e32 v110, v60
	v_mov_b32_e32 v111, v60
	v_mov_b32_e32 v112, v60
	v_mov_b32_e32 v113, v60
	v_mov_b32_e32 v114, v60
	v_mov_b32_e32 v115, v60
	v_mov_b32_e32 v116, v60
	v_mov_b32_e32 v117, v60
	v_mov_b32_e32 v118, v60
	v_mov_b32_e32 v119, v60
	v_mov_b32_e32 v120, v60
	v_mov_b32_e32 v121, v60
	v_mov_b32_e32 v122, v60
	v_mov_b32_e32 v123, v60
	v_mov_b32_e32 v124, v60
	v_mov_b32_e32 v125, v60
	v_mov_b32_e32 v126, v60
	v_mov_b32_e32 v127, v60
	v_lshl_add_u64 v[192:193], v[190:191], 0, s[8:9]
	v_lshl_add_u64 v[194:195], v[190:191], 0, s[18:19]
	v_mov_b32_e32 v194, 0
	ds_read_b64 v[192:193], v194
	v_and_b32_e32 v195, 63, v196
	v_lshrrev_b32_e32 v239, 3, v195
	v_and_b32_e32 v236, 7, v195
	v_xor_b32_e32 v236, v236, v239
	v_lshlrev_b32_e32 v236, 4, v236
	v_mul_u32_u24_e32 v239, 2048, v239
	v_add_u32_e32 v226, v239, v236
	v_add_u32_e32 v227, 65536, v226
	v_add_u32_e32 v248, 131072, v226
	v_add_u32_e32 v249, 196608, v226
	v_add_u32_e32 v247, 262144, v226
	v_add_u32_e32 v244, 327680, v226
	v_add_u32_e32 v245, 393216, v226
	v_add_u32_e32 v246, 458752, v226
	v_lshrrev_b32_e32 v239, 6, v196
	v_lshrrev_b32_e32 v236, 1, v239
	v_and_b32_e32 v239, 1, v239
	v_and_b32_e32 v237, 15, v195
	v_lshrrev_b32_e32 v238, 4, v195
	v_and_b32_e32 v235, 7, v237
	v_xor_b32_e32 v238, v238, v235
	v_lshlrev_b32_e32 v238, 4, v238
	v_lshlrev_b32_e32 v236, 7, v236
	v_add_u32_e32 v236, v236, v237
	v_lshl_add_u32 v243, v236, 7, v238
	v_xor_b32_e32 v240, 64, v243
	v_lshlrev_b32_e32 v239, 6, v239
	v_add_u32_e32 v239, v239, v237
	v_lshl_add_u32 v241, v239, 7, v238
	v_add_u32_e32 v241, 65536, v241
	v_xor_b32_e32 v242, 64, v241
	v_lshrrev_b32_e32 v239, 6, v196
	v_lshlrev_b32_e32 v239, 10, v239
	s_nop 0
	v_readfirstlane_b32 s4, v239
	s_waitcnt lgkmcnt(0)
	s_barrier
	s_add_u32 m0, s4, 0
	s_nop 0
	global_load_lds_dwordx4 v226, s[98:99]
	s_add_u32 m0, s4, 4096
	s_nop 0
	global_load_lds_dwordx4 v227, s[98:99]
	s_add_u32 m0, s4, 8192
	s_nop 0
	global_load_lds_dwordx4 v248, s[98:99]
	s_add_u32 m0, s4, 12288
	s_nop 0
	global_load_lds_dwordx4 v249, s[98:99]
	s_add_u32 m0, s4, 16384
	s_nop 0
	global_load_lds_dwordx4 v247, s[98:99]
	s_add_u32 m0, s4, 20480
	s_nop 0
	global_load_lds_dwordx4 v244, s[98:99]
	s_add_u32 m0, s4, 24576
	s_nop 0
	global_load_lds_dwordx4 v245, s[98:99]
	s_add_u32 m0, s4, 28672
	s_nop 0
	global_load_lds_dwordx4 v246, s[98:99]
	s_add_u32 m0, s4, 65536
	s_nop 0
	global_load_lds_dwordx4 v226, s[100:101]
	s_add_u32 m0, s4, 69632
	s_nop 0
	global_load_lds_dwordx4 v227, s[100:101]
	s_add_u32 m0, s4, 73728
	s_nop 0
	global_load_lds_dwordx4 v248, s[100:101]
	s_add_u32 m0, s4, 77824
	s_nop 0
	global_load_lds_dwordx4 v249, s[100:101]
	s_add_u32 s98, s98, 0x80
	s_addc_u32 s99, s99, 0
	s_add_u32 s100, s100, 0x80
	s_addc_u32 s101, s101, 0
	s_mov_b32 s5, 7

.LBB0_1242:
	s_ashr_i32 s0, s29, 6
	s_lshr_b32 s1, s84, 3
	s_cmp_eq_u32 s0, 2
	s_cbranch_scc1 .Lxb11_ns
	s_lshr_b32 s2, s1, 2
	s_lshr_b32 s3, s1, 5
	s_xor_b32 s2, s2, s3
	s_and_b32 s2, s2, 1
	s_mul_i32 s2, s2, 36
	s_xor_b32 s1, s1, s2
.Lxb11_ns:
	s_lshl_b32 s2, s0, 6
	s_add_i32 s1, s1, s2
	s_mov_b32 s4, 2
	s_cmp_gt_i32 s1, 167
	s_cbranch_scc1 .LBB0_1569
	s_and_b32 s2, s84, 7
	s_mul_i32 s2, s2, 168
	s_add_i32 s1, s1, s2
	s_lshr_b32 s2, s1, 5
	s_and_b32 s1, s1, 31
	s_mul_hi_u32 s3, s2, 0x24924925
	s_mul_i32 s5, s3, 7
	s_sub_i32 s5, s2, s5
	s_lshl_b32 s2, s3, 2
	s_lshr_b32 s6, s5, 1
	s_add_i32 s2, s2, s6
	s_and_b32 s5, s5, 1
	s_lshl_b32 s5, s5, 2
	s_lshr_b32 s6, s1, 3
	s_add_i32 s5, s5, s6
	s_lshl_b32 s5, s5, 3
	s_and_b32 s1, s1, 7
	s_or_b32 s5, s5, s1
	s_lshl_b32 s0, s0, 6
	s_or_b32 s29, s0, s5
	s_lshl_b32 s30, s29, 8
	s_ashr_i32 s0, s2, 31
	s_lshr_b32 s0, s0, 30
	s_add_i32 s0, s2, s0
	s_and_b32 s1, s0, 0x1ffffffc
	s_sub_i32 s1, s2, s1
	s_lshl_b32 s1, s1, 3
	s_bfe_u32 s3, s29, 0x30003
	s_or_b32 s6, s1, s3
	s_cmp_gt_i32 s6, 27
	s_mov_b32 s4, 4
	s_cbranch_scc1 .LBB0_1569
	s_ashr_i32 s7, s0, 2
	s_lshl_b32 s0, s29, 8
	s_lshl_b32 s11, s7, 11
	s_and_b32 s0, s0, 0x700
	s_or_b32 s0, s11, s0
	s_ashr_i32 s1, s0, 31
	s_lshl_b64 s[4:5], s[0:1], 11
	v_lshl_add_u64 v[0:1], v[182:183], 0, s[4:5]
	v_add_co_u32_e32 v2, vcc, 0x10000, v0
	s_lshl_b32 s22, s6, 7
	s_nop 0
	v_addc_co_u32_e32 v3, vcc, 0, v1, vcc
	s_nop 0
	v_readfirstlane_b32 s98, v0
	v_readfirstlane_b32 s99, v1
	v_add_co_u32_e32 v2, vcc, 0x20000, v0
	s_ashr_i32 s23, s22, 31
	s_nop 0
	v_addc_co_u32_e32 v3, vcc, 0, v1, vcc
	v_add_co_u32_e32 v4, vcc, 0x30000, v0
	s_lshl_b64 s[8:9], s[22:23], 11
	s_nop 0
	v_addc_co_u32_e32 v5, vcc, 0, v1, vcc
	v_add_co_u32_e32 v2, vcc, 0x40000, v0
	s_lshl_b32 s1, s2, 3
	s_nop 0
	v_addc_co_u32_e32 v3, vcc, 0, v1, vcc
	v_add_co_u32_e32 v4, vcc, 0x50000, v0
	s_or_b32 s1, s1, s3
	s_nop 0
	v_addc_co_u32_e32 v5, vcc, 0, v1, vcc
	v_add_co_u32_e32 v2, vcc, 0x60000, v0
	s_lshl_b32 s2, s7, 5
	s_nop 0
	v_addc_co_u32_e32 v3, vcc, 0, v1, vcc
	v_add_co_u32_e32 v0, vcc, 0x70000, v0
	s_and_b32 s10, s30, 0x700
	s_nop 0
	v_addc_co_u32_e32 v1, vcc, 0, v1, vcc
	v_lshl_add_u64 v[0:1], v[184:185], 0, s[8:9]
	v_add_co_u32_e32 v2, vcc, s34, v0
	s_sub_i32 s1, s1, s2
	s_nop 0
	v_addc_co_u32_e32 v3, vcc, 0, v1, vcc
	s_nop 0
	v_readfirstlane_b32 s100, v0
	v_readfirstlane_b32 s101, v1
	v_add_co_u32_e32 v2, vcc, s35, v0
	s_or_b32 s4, s11, s10
	s_nop 0
	v_addc_co_u32_e32 v3, vcc, 0, v1, vcc
	v_add_co_u32_e32 v0, vcc, s38, v0
	s_lshl_b32 s2, s1, 7
	s_nop 0
	v_addc_co_u32_e32 v1, vcc, 0, v1, vcc
	s_ashr_i32 s5, s4, 31
	s_ashr_i32 s3, s2, 31
	s_lshl_b64 s[4:5], s[4:5], 11
	s_lshl_b64 s[2:3], s[2:3], 11
	v_mov_b32_e32 v76, 0
	v_lshl_add_u64 v[188:189], v[186:187], 0, s[4:5]
	v_lshl_add_u64 v[190:191], v[186:187], 0, s[2:3]
	s_mov_b64 s[2:3], 0
	v_mov_b32_e32 v77, v76
	v_mov_b32_e32 v78, v76
	v_mov_b32_e32 v79, v76
	v_mov_b32_e32 v0, v76
	v_mov_b32_e32 v1, v76
	v_mov_b32_e32 v2, v76
	v_mov_b32_e32 v3, v76
	v_mov_b32_e32 v4, v76
	v_mov_b32_e32 v5, v76
	v_mov_b32_e32 v6, v76
	v_mov_b32_e32 v7, v76
	v_mov_b32_e32 v8, v76
	v_mov_b32_e32 v9, v76
	v_mov_b32_e32 v10, v76
	v_mov_b32_e32 v11, v76
	v_mov_b32_e32 v12, v76
	v_mov_b32_e32 v13, v76
	v_mov_b32_e32 v14, v76
	v_mov_b32_e32 v15, v76
	v_mov_b32_e32 v16, v76
	v_mov_b32_e32 v17, v76
	v_mov_b32_e32 v18, v76
	v_mov_b32_e32 v19, v76
	v_mov_b32_e32 v20, v76
	v_mov_b32_e32 v21, v76
	v_mov_b32_e32 v22, v76
	v_mov_b32_e32 v23, v76
	v_mov_b32_e32 v24, v76
	v_mov_b32_e32 v25, v76
	v_mov_b32_e32 v26, v76
	v_mov_b32_e32 v27, v76
	v_mov_b32_e32 v28, v76
	v_mov_b32_e32 v29, v76
	v_mov_b32_e32 v30, v76
	v_mov_b32_e32 v31, v76
	v_mov_b32_e32 v32, v76
	v_mov_b32_e32 v33, v76
	v_mov_b32_e32 v34, v76
	v_mov_b32_e32 v35, v76
	s_waitcnt vmcnt(24)
	v_mov_b32_e32 v36, v76
	v_mov_b32_e32 v37, v76
	v_mov_b32_e32 v38, v76
	v_mov_b32_e32 v39, v76
	s_waitcnt vmcnt(23)
	v_mov_b32_e32 v40, v76
	v_mov_b32_e32 v41, v76
	v_mov_b32_e32 v42, v76
	v_mov_b32_e32 v43, v76
	s_waitcnt vmcnt(22)
	v_mov_b32_e32 v44, v76
	v_mov_b32_e32 v45, v76
	v_mov_b32_e32 v46, v76
	v_mov_b32_e32 v47, v76
	s_waitcnt vmcnt(21)
	v_mov_b32_e32 v48, v76
	v_mov_b32_e32 v49, v76
	v_mov_b32_e32 v50, v76
	v_mov_b32_e32 v51, v76
	s_waitcnt vmcnt(20)
	v_mov_b32_e32 v52, v76
	v_mov_b32_e32 v53, v76
	v_mov_b32_e32 v54, v76
	v_mov_b32_e32 v55, v76
	v_mov_b32_e32 v56, v76
	v_mov_b32_e32 v57, v76
	v_mov_b32_e32 v58, v76
	v_mov_b32_e32 v59, v76
	v_mov_b32_e32 v60, v76
	v_mov_b32_e32 v61, v76
	v_mov_b32_e32 v62, v76
	v_mov_b32_e32 v63, v76
	v_mov_b32_e32 v64, v76
	v_mov_b32_e32 v65, v76
	v_mov_b32_e32 v66, v76
	v_mov_b32_e32 v67, v76
	v_mov_b32_e32 v68, v76
	v_mov_b32_e32 v69, v76
	v_mov_b32_e32 v70, v76
	v_mov_b32_e32 v71, v76
	v_mov_b32_e32 v72, v76
	v_mov_b32_e32 v73, v76
	v_mov_b32_e32 v74, v76
	v_mov_b32_e32 v75, v76
	v_mov_b32_e32 v80, v76
	v_mov_b32_e32 v81, v76
	v_mov_b32_e32 v82, v76
	v_mov_b32_e32 v83, v76
	v_mov_b32_e32 v84, v76
	v_mov_b32_e32 v85, v76
	v_mov_b32_e32 v86, v76
	v_mov_b32_e32 v87, v76
	v_mov_b32_e32 v88, v76
	v_mov_b32_e32 v89, v76
	v_mov_b32_e32 v90, v76
	v_mov_b32_e32 v91, v76
	v_mov_b32_e32 v92, v76
	v_mov_b32_e32 v93, v76
	v_mov_b32_e32 v94, v76
	v_mov_b32_e32 v95, v76
	v_mov_b32_e32 v96, v76
	v_mov_b32_e32 v97, v76
	v_mov_b32_e32 v98, v76
	v_mov_b32_e32 v99, v76
	v_mov_b32_e32 v100, v76
	v_mov_b32_e32 v101, v76
	v_mov_b32_e32 v102, v76
	v_mov_b32_e32 v103, v76
	v_mov_b32_e32 v104, v76
	v_mov_b32_e32 v105, v76
	v_mov_b32_e32 v106, v76
	v_mov_b32_e32 v107, v76
	v_mov_b32_e32 v108, v76
	v_mov_b32_e32 v109, v76
	v_mov_b32_e32 v110, v76
	v_mov_b32_e32 v111, v76
	v_mov_b32_e32 v112, v76
	v_mov_b32_e32 v113, v76
	v_mov_b32_e32 v114, v76
	v_mov_b32_e32 v115, v76
	v_mov_b32_e32 v116, v76
	v_mov_b32_e32 v117, v76
	v_mov_b32_e32 v118, v76
	v_mov_b32_e32 v119, v76
	v_mov_b32_e32 v120, v76
	v_mov_b32_e32 v121, v76
	v_mov_b32_e32 v122, v76
	v_mov_b32_e32 v123, v76
	v_mov_b32_e32 v124, v76
	v_mov_b32_e32 v125, v76
	v_mov_b32_e32 v126, v76
	v_mov_b32_e32 v127, v76
	v_mov_b32_e32 v234, 0
	ds_read_b64 v[232:233], v234
	v_and_b32_e32 v235, 63, v196
	v_lshrrev_b32_e32 v250, 3, v235
	v_and_b32_e32 v247, 7, v235
	v_xor_b32_e32 v247, v247, v250
	v_lshlrev_b32_e32 v247, 4, v247
	v_mul_u32_u24_e32 v250, 2048, v250
	v_add_u32_e32 v134, v250, v247
	v_add_u32_e32 v142, 65536, v134
	v_add_u32_e32 v143, 131072, v134
	v_add_u32_e32 v180, 196608, v134
	v_add_u32_e32 v215, 262144, v134
	v_add_u32_e32 v216, 327680, v134
	v_add_u32_e32 v217, 393216, v134
	v_add_u32_e32 v218, 458752, v134
	v_lshrrev_b32_e32 v250, 6, v196
	v_lshrrev_b32_e32 v247, 1, v250
	v_and_b32_e32 v250, 1, v250
	v_and_b32_e32 v244, 15, v235
	v_lshrrev_b32_e32 v245, 4, v235
	v_and_b32_e32 v246, 7, v244
	v_xor_b32_e32 v245, v245, v246
	v_lshlrev_b32_e32 v245, 4, v245
	v_lshlrev_b32_e32 v247, 7, v247
	v_add_u32_e32 v247, v247, v244
	v_lshl_add_u32 v252, v247, 7, v245
	v_xor_b32_e32 v251, 64, v252
	v_lshlrev_b32_e32 v250, 6, v250
	v_add_u32_e32 v250, v250, v244
	v_lshl_add_u32 v248, v250, 7, v245
	v_add_u32_e32 v248, 65536, v248
	v_xor_b32_e32 v249, 64, v248
	v_lshrrev_b32_e32 v250, 6, v196
	v_lshlrev_b32_e32 v250, 10, v250
	s_nop 0
	v_readfirstlane_b32 s2, v250
	s_waitcnt lgkmcnt(0)
	s_barrier
	s_add_u32 m0, s2, 0
	s_nop 0
	global_load_lds_dwordx4 v134, s[98:99]
	s_add_u32 m0, s2, 4096
	s_nop 0
	global_load_lds_dwordx4 v142, s[98:99]
	s_add_u32 m0, s2, 8192
	s_nop 0
	global_load_lds_dwordx4 v143, s[98:99]
	s_add_u32 m0, s2, 12288
	s_nop 0
	global_load_lds_dwordx4 v180, s[98:99]
	s_add_u32 m0, s2, 16384
	s_nop 0
	global_load_lds_dwordx4 v215, s[98:99]
	s_add_u32 m0, s2, 20480
	s_nop 0
	global_load_lds_dwordx4 v216, s[98:99]
	s_add_u32 m0, s2, 24576
	s_nop 0
	global_load_lds_dwordx4 v217, s[98:99]
	s_add_u32 m0, s2, 28672
	s_nop 0
	global_load_lds_dwordx4 v218, s[98:99]
	s_add_u32 m0, s2, 65536
	s_nop 0
	global_load_lds_dwordx4 v134, s[100:101]
	s_add_u32 m0, s2, 69632
	s_nop 0
	global_load_lds_dwordx4 v142, s[100:101]
	s_add_u32 m0, s2, 73728
	s_nop 0
	global_load_lds_dwordx4 v143, s[100:101]
	s_add_u32 m0, s2, 77824
	s_nop 0
	global_load_lds_dwordx4 v180, s[100:101]
	s_add_u32 s98, s98, 0x80
	s_addc_u32 s99, s99, 0
	s_add_u32 s100, s100, 0x80
	s_addc_u32 s101, s101, 0
	s_mov_b32 s3, 7
